# scan2 split: first half on CUs 128-255 during S5Y phase, second half on CUs 130-255 alongside GLU on 130 CUs
# speedup vs baseline: 1.0138x; 1.0124x over previous
; __device__ __forceinline__ int opaque_tid() { int t = threadIdx.x; asm volatile("" : "+v"(t)); return t; }
; __device__ __forceinline__ void lru_scan2(bf16_t* p5, const bf16_t* bbuf, const float* agg) {
;     const int gt = blockIdx.x * 512 + opaque_tid(), NGT = gridDim.x * 512;
;     for (int it = gt; it < NB * NCH64 * 512; it += NGT) {
;         const int cp = it & 511, bc = it >> 9; const int b = bc / NCH64, c = bc - b * NCH64; const size_t m0 = (size_t)b * TP + c * 64;
;         float h0 = 0.f, h1 = 0.f;
;         for (int cc0 = 0; cc0 < c; cc0 += 8) {
.LBB0_945:
	s_cmpk_lt_u32 s2, 0x80
	s_cbranch_scc1 .Lscan2_skip
	s_sub_u32 s100, s2, 0x80
	s_lshl_b32 s100, s100, 9
	s_mov_b32 s101, 0x20800
	s_mov_b32 s4, 0x10000
	v_writelane_b32 v255, s4, 50
	s_nop 1
.Lscan2_entry:
	v_mov_b32_e32 v0, v163
	v_mov_b32_e32 v2, v162
	s_mov_b32 s4, s100
	v_readfirstlane_b32 s1, v0
	v_mov_b32_e32 v0, v1
	v_readfirstlane_b32 s0, v2
	v_mov_b32_e32 v0, v208
	s_waitcnt vmcnt(0)
	v_add_u32_e32 v58, s4, v0
	v_readlane_b32 s4, v255, 50
	s_nop 1
	v_cmp_gt_i32_e32 vcc, s4, v58
	s_and_saveexec_b64 s[4:5], vcc
	s_cbranch_execz .Lscan2_done
	v_and_b32_e32 v0, 0x1ff, v0
	v_lshlrev_b32_e32 v34, 2, v0
	v_lshlrev_b32_e32 v0, 4, v0
	v_lshl_add_u64 v[2:3], s[0:1], 0, v[0:1]
	s_mov_b64 s[14:15], 0x2b600000
	v_mov_b32_e32 v35, v1
	v_lshl_add_u64 v[36:37], v[2:3], 0, s[14:15]
	s_mov_b64 s[14:15], 0

; __device__ __forceinline__ unsigned cvt_pk_bf16(float lo, float hi) { unsigned r; asm volatile("v_cvt_pk_bf16_f32 %0, %1, %2" : "=v"(r) : "v"(lo), "v"(hi)); return r; }
; __device__ __forceinline__ float bf_lo(unsigned w) { return __uint_as_float(w << 16); }
; __device__ __forceinline__ float bf_hi(unsigned w) { return __uint_as_float(w & 0xffff0000u); }
; __device__ __forceinline__ float gelu_tanh(float x) { const float u = 1.5957691216057308f * (x + 0.044715f * x * x * x); return x * sigmoidf_(u); }
; __device__ __forceinline__ void lru_scan2(bf16_t* p5, const bf16_t* bbuf, const float* agg) {
;     ...
;         for (int t0 = 0; t0 < 64; t0 += 8) {
;             unsigned lw[8], bw[8], gw[8];
; #pragma unroll
;             for (int k = 0; k < 8; ++k) { lw[k] = *(const unsigned*)(p5 + (m0 + t0 + k) * LDP + C_AX + 2 * cp); bw[k] = *(const unsigned*)(bbuf + (m0 + t0 + k) * 1024 + 2 * cp);
;                 gw[k] = *(const unsigned*)(p5 + (m0 + t0 + k) * LDP + C_AG + 2 * cp); }
; #pragma unroll
;             for (int k = 0; k < 8; ++k) { h0 = __expf(bf_lo(lw[k])) * h0 + bf_lo(bw[k]); h1 = __expf(bf_hi(lw[k])) * h1 + bf_hi(bw[k]);
;                 gw[k] = cvt_pk_bf16(h0 * gelu_tanh(bf_lo(gw[k])), h1 * gelu_tanh(bf_hi(gw[k]))); }
.LBB0_966:
	v_lshl_add_u64 v[20:21], v[2:3], 0, v[34:35]
	v_add_co_u32_e32 v6, vcc, 0x8900000, v20
	v_lshl_add_u64 v[22:23], v[4:5], 0, v[34:35]
	s_nop 0
	v_addc_co_u32_e32 v7, vcc, 0, v21, vcc
	global_load_dword v0, v[6:7], off offset:2048
	v_add_co_u32_e32 v8, vcc, 0x1ef00000, v22
	s_add_i32 s16, s16, 8
	s_nop 0
	v_addc_co_u32_e32 v9, vcc, 0, v23, vcc
	global_load_dword v26, v[8:9], off
	global_load_dword v27, v[6:7], off
	v_add_co_u32_e32 v10, vcc, 0x8903000, v20
	s_mov_b64 s[18:19], 0x4000
	s_nop 0
	v_addc_co_u32_e32 v11, vcc, 0, v21, vcc
	global_load_dword v28, v[10:11], off
	global_load_dword v30, v[8:9], off offset:2048
	v_add_co_u32_e32 v8, vcc, 0x8902000, v20
	v_lshl_add_u64 v[2:3], v[2:3], 0, s[12:13]
	s_nop 0
	v_addc_co_u32_e32 v9, vcc, 0, v21, vcc
	global_load_dword v31, v[8:9], off offset:2048
	v_add_co_u32_e32 v10, vcc, 0x8905000, v20
	v_lshl_add_u64 v[4:5], v[4:5], 0, s[18:19]
	s_nop 0
	v_addc_co_u32_e32 v11, vcc, 0, v21, vcc
	v_add_co_u32_e32 v12, vcc, 0x1ef01000, v22
	global_load_dword v32, v[10:11], off offset:2048
	s_nop 0
	v_addc_co_u32_e32 v13, vcc, 0, v23, vcc
	v_add_co_u32_e32 v14, vcc, 0x8908000, v20
	global_load_dword v40, v[12:13], off
	global_load_dword v41, v[10:11], off
	v_addc_co_u32_e32 v15, vcc, 0, v21, vcc
	global_load_dword v42, v[14:15], off
	global_load_dword v43, v[12:13], off offset:2048
	v_add_co_u32_e32 v12, vcc, 0x8907000, v20
	s_cmp_gt_u32 s16, 55
	s_nop 0
	v_addc_co_u32_e32 v13, vcc, 0, v21, vcc
	v_add_co_u32_e32 v14, vcc, 0x890a000, v20
	global_load_dword v44, v[12:13], off offset:2048
	s_nop 0
	v_addc_co_u32_e32 v15, vcc, 0, v21, vcc
	v_add_co_u32_e32 v16, vcc, 0x1ef02000, v22
	global_load_dword v45, v[14:15], off offset:2048
	s_nop 0
	v_addc_co_u32_e32 v17, vcc, 0, v23, vcc
	v_add_co_u32_e32 v18, vcc, 0x890d000, v20
	global_load_dword v46, v[16:17], off
	global_load_dword v47, v[14:15], off
	v_addc_co_u32_e32 v19, vcc, 0, v21, vcc
	global_load_dword v48, v[18:19], off
	global_load_dword v49, v[16:17], off offset:2048
	v_add_co_u32_e32 v16, vcc, 0x890c000, v20
	s_waitcnt vmcnt(12)
	v_lshlrev_b32_e32 v29, 16, v30
	v_addc_co_u32_e32 v17, vcc, 0, v21, vcc
	v_add_co_u32_e32 v18, vcc, 0x890f000, v20
	global_load_dword v50, v[16:17], off offset:2048
	s_nop 0
	v_addc_co_u32_e32 v19, vcc, 0, v21, vcc
	v_add_co_u32_e32 v22, vcc, 0x1ef03000, v22
	global_load_dword v51, v[18:19], off offset:2048
	s_nop 0
	v_addc_co_u32_e32 v23, vcc, 0, v23, vcc
	v_add_co_u32_e32 v24, vcc, 0x8912000, v20
	global_load_dword v52, v[22:23], off
	global_load_dword v53, v[18:19], off
	v_addc_co_u32_e32 v25, vcc, 0, v21, vcc
	global_load_dword v54, v[24:25], off
	global_load_dword v55, v[22:23], off offset:2048
	v_lshlrev_b32_e32 v22, 16, v0
	v_and_b32_e32 v0, 0xffff0000, v0
	v_mul_f32_e32 v22, 0x3fb8aa3b, v22
	v_mul_f32_e32 v0, 0x3fb8aa3b, v0
	v_exp_f32_e32 v23, v22
	v_exp_f32_e32 v22, v0
	v_lshlrev_b32_e32 v0, 16, v27
	v_lshlrev_b32_e32 v25, 16, v26
	v_and_b32_e32 v24, 0xffff0000, v26
	v_mul_f32_e32 v26, 0x3d372713, v0
	v_mul_f32_e32 v26, v26, v0
	v_fma_f32 v26, v26, v0, v0
	v_mul_f32_e32 v26, 0x3fcc422a, v26
	v_mul_f32_e32 v26, 0xbfb8aa3b, v26
	v_exp_f32_e32 v26, v26
	v_add_co_u32_e32 v20, vcc, 0x8911000, v20
	v_pk_fma_f32 v[22:23], v[38:39], v[22:23], v[24:25]
	v_add_f32_e32 v26, 1.0, v26
	v_rcp_f32_e32 v26, v26
	v_addc_co_u32_e32 v21, vcc, 0, v21, vcc
	global_load_dword v56, v[20:21], off offset:2048
	v_mul_f32_e32 v0, v26, v0
	v_and_b32_e32 v26, 0xffff0000, v27
	v_mul_f32_e32 v27, 0x3d372713, v26
	v_mul_f32_e32 v27, v27, v26
	v_fma_f32 v27, v27, v26, v26
	v_mul_f32_e32 v27, 0x3fcc422a, v27
	v_mul_f32_e32 v27, 0xbfb8aa3b, v27
	v_exp_f32_e32 v27, v27
	v_mul_f32_e32 v0, v23, v0
	s_waitcnt vmcnt(10)
	v_lshlrev_b32_e32 v39, 16, v46
	v_and_b32_e32 v38, 0xffff0000, v46
	v_add_f32_e32 v27, 1.0, v27
	v_rcp_f32_e32 v27, v27
	s_waitcnt vmcnt(4)
	v_and_b32_e32 v46, 0xffff0000, v52
	v_mul_f32_e32 v57, v27, v26
	v_lshlrev_b32_e32 v26, 16, v28
	v_mul_f32_e32 v26, 0x3fb8aa3b, v26
	v_exp_f32_e32 v27, v26
	v_and_b32_e32 v26, 0xffff0000, v28
	v_and_b32_e32 v28, 0xffff0000, v30
	v_lshlrev_b32_e32 v30, 16, v31
	v_mul_f32_e32 v33, 0x3d372713, v30
	v_mul_f32_e32 v33, v33, v30
	v_fma_f32 v33, v33, v30, v30
	v_mul_f32_e32 v33, 0x3fcc422a, v33
	v_mul_f32_e32 v33, 0xbfb8aa3b, v33
	v_exp_f32_e32 v33, v33
	v_mul_f32_e32 v26, 0x3fb8aa3b, v26
	v_exp_f32_e32 v26, v26
	v_mul_f32_e32 v24, v22, v57
	v_add_f32_e32 v33, 1.0, v33
	v_rcp_f32_e32 v33, v33
	v_pk_fma_f32 v[22:23], v[22:23], v[26:27], v[28:29]
	v_cvt_pk_bf16_f32 v0, v0, v24
	v_lshlrev_b32_e32 v28, 16, v44
	v_mul_f32_e32 v59, v33, v30
	v_and_b32_e32 v30, 0xffff0000, v31
	v_mul_f32_e32 v31, 0x3d372713, v30
	v_mul_f32_e32 v31, v31, v30
	v_fma_f32 v31, v31, v30, v30
	v_mul_f32_e32 v31, 0x3fcc422a, v31
	v_mul_f32_e32 v31, 0xbfb8aa3b, v31
	v_exp_f32_e32 v31, v31
	v_mul_f32_e32 v24, v23, v59
	v_lshlrev_b32_e32 v33, 16, v40
	v_mul_f32_e32 v29, 0x3d372713, v28
	v_add_f32_e32 v31, 1.0, v31
	v_rcp_f32_e32 v31, v31
	v_mul_f32_e32 v29, v29, v28
	v_fma_f32 v29, v29, v28, v28
	v_mul_f32_e32 v29, 0x3fcc422a, v29
	v_mul_f32_e32 v60, v31, v30
	v_mul_f32_e32 v25, v22, v60
	v_cvt_pk_bf16_f32 v57, v24, v25
	v_lshlrev_b32_e32 v24, 16, v41
	v_mul_f32_e32 v25, 0x3d372713, v24
	v_mul_f32_e32 v25, v25, v24
	v_fma_f32 v25, v25, v24, v24
	v_mul_f32_e32 v25, 0x3fcc422a, v25
	v_mul_f32_e32 v25, 0xbfb8aa3b, v25
	v_exp_f32_e32 v25, v25
	v_lshlrev_b32_e32 v30, 16, v32
	v_mul_f32_e32 v30, 0x3fb8aa3b, v30
	v_exp_f32_e32 v31, v30
	v_add_f32_e32 v25, 1.0, v25
	v_rcp_f32_e32 v25, v25
	v_and_b32_e32 v30, 0xffff0000, v32
	v_and_b32_e32 v32, 0xffff0000, v40
	v_lshlrev_b32_e32 v40, 16, v47
	v_mul_f32_e32 v59, v25, v24
; __device__ __forceinline__ unsigned cvt_pk_bf16(float lo, float hi) { unsigned r; asm volatile("v_cvt_pk_bf16_f32 %0, %1, %2" : "=v"(r) : "v"(lo), "v"(hi)); return r; }
; __device__ __forceinline__ float bf_lo(unsigned w) { return __uint_as_float(w << 16); }
; __device__ __forceinline__ float bf_hi(unsigned w) { return __uint_as_float(w & 0xffff0000u); }
; __device__ __forceinline__ float gelu_tanh(float x) { const float u = 1.5957691216057308f * (x + 0.044715f * x * x * x); return x * sigmoidf_(u); }
; __device__ __forceinline__ void lru_scan2(bf16_t* p5, const bf16_t* bbuf, const float* agg) {
;     ...
;             for (int k = 0; k < 8; ++k) { lw[k] = *(const unsigned*)(p5 + (m0 + t0 + k) * LDP + C_AX + 2 * cp); bw[k] = *(const unsigned*)(bbuf + (m0 + t0 + k) * 1024 + 2 * cp);
;                 gw[k] = *(const unsigned*)(p5 + (m0 + t0 + k) * LDP + C_AG + 2 * cp); }
; #pragma unroll
;             for (int k = 0; k < 8; ++k) { h0 = __expf(bf_lo(lw[k])) * h0 + bf_lo(bw[k]); h1 = __expf(bf_hi(lw[k])) * h1 + bf_hi(bw[k]);
;                 gw[k] = cvt_pk_bf16(h0 * gelu_tanh(bf_lo(gw[k])), h1 * gelu_tanh(bf_hi(gw[k]))); }
; #pragma unroll
;             for (int k = 0; k < 8; ++k) *(unsigned*)(p5 + (m0 + t0 + k) * LDP + C_AG + 2 * cp) = gw[k];
;         }
;     }
; __device__ __forceinline__ void xcd_barrier(const XcdBarrier& b) {
;     asm volatile("s_waitcnt vmcnt(0)" ::: "memory");
;     __syncthreads();
;     if (threadIdx.x == 0) {
;         unsigned* bar = b.bar;
;         __builtin_amdgcn_s_waitcnt(0);
;         unsigned nloc = b.st[0], nx = b.st[1];
;         if (nloc == 0u) { xcd_barrier_complete(bar, b.x, nloc, nx); b.st[0] = nloc; b.st[1] = nx; }
	v_and_b32_e32 v24, 0xffff0000, v41
	v_mul_f32_e32 v41, 0x3d372713, v40
	v_mul_f32_e32 v41, v41, v40
	v_fma_f32 v41, v41, v40, v40
	v_mul_f32_e32 v41, 0x3fcc422a, v41
	v_mul_f32_e32 v29, 0xbfb8aa3b, v29
	v_mul_f32_e32 v41, 0xbfb8aa3b, v41
	v_exp_f32_e32 v29, v29
	v_exp_f32_e32 v41, v41
	v_mul_f32_e32 v25, 0x3d372713, v24
	v_mul_f32_e32 v25, v25, v24
	v_add_f32_e32 v29, 1.0, v29
	v_add_f32_e32 v41, 1.0, v41
	v_rcp_f32_e32 v29, v29
	v_rcp_f32_e32 v41, v41
	v_fma_f32 v25, v25, v24, v24
	v_mul_f32_e32 v25, 0x3fcc422a, v25
	v_mul_f32_e32 v61, v29, v28
	v_and_b32_e32 v28, 0xffff0000, v44
	v_mul_f32_e32 v63, v41, v40
	v_and_b32_e32 v40, 0xffff0000, v47
	v_mul_f32_e32 v29, 0x3d372713, v28
	v_mul_f32_e32 v41, 0x3d372713, v40
	v_mul_f32_e32 v29, v29, v28
	v_mul_f32_e32 v41, v41, v40
	v_fma_f32 v29, v29, v28, v28
	v_fma_f32 v41, v41, v40, v40
	v_mul_f32_e32 v29, 0x3fcc422a, v29
	v_mul_f32_e32 v41, 0x3fcc422a, v41
	v_mul_f32_e32 v29, 0xbfb8aa3b, v29
	v_mul_f32_e32 v41, 0xbfb8aa3b, v41
	v_mul_f32_e32 v25, 0xbfb8aa3b, v25
	v_exp_f32_e32 v29, v29
	v_exp_f32_e32 v41, v41
	v_exp_f32_e32 v25, v25
	v_lshlrev_b32_e32 v44, 16, v50
	v_add_f32_e32 v29, 1.0, v29
	v_add_f32_e32 v41, 1.0, v41
	v_add_f32_e32 v25, 1.0, v25
	v_rcp_f32_e32 v29, v29
	v_rcp_f32_e32 v41, v41
	v_rcp_f32_e32 v25, v25
	v_lshlrev_b32_e32 v27, 16, v43
	v_mul_f32_e32 v62, v29, v28
	v_lshlrev_b32_e32 v28, 16, v45
	v_mul_f32_e32 v64, v41, v40
	v_lshlrev_b32_e32 v40, 16, v48
	v_mul_f32_e32 v60, v25, v24
	v_lshlrev_b32_e32 v24, 16, v42
	v_mul_f32_e32 v28, 0x3fb8aa3b, v28
	v_mul_f32_e32 v40, 0x3fb8aa3b, v40
	v_mul_f32_e32 v24, 0x3fb8aa3b, v24
	v_exp_f32_e32 v29, v28
	v_and_b32_e32 v28, 0xffff0000, v45
	v_exp_f32_e32 v41, v40
	v_and_b32_e32 v40, 0xffff0000, v48
	v_mul_f32_e32 v45, 0x3d372713, v44
	s_waitcnt vmcnt(3)
	v_lshlrev_b32_e32 v48, 16, v53
	v_exp_f32_e32 v25, v24
	v_and_b32_e32 v24, 0xffff0000, v42
	v_and_b32_e32 v26, 0xffff0000, v43
	v_lshlrev_b32_e32 v43, 16, v49
	v_and_b32_e32 v42, 0xffff0000, v49
	v_mul_f32_e32 v45, v45, v44
	v_mul_f32_e32 v49, 0x3d372713, v48
	v_fma_f32 v45, v45, v44, v44
	v_mul_f32_e32 v49, v49, v48
	v_mul_f32_e32 v45, 0x3fcc422a, v45
	v_fma_f32 v49, v49, v48, v48
	v_mul_f32_e32 v45, 0xbfb8aa3b, v45
	v_mul_f32_e32 v49, 0x3fcc422a, v49
	v_exp_f32_e32 v45, v45
	v_mul_f32_e32 v49, 0xbfb8aa3b, v49
	v_exp_f32_e32 v49, v49
	v_lshlrev_b32_e32 v47, 16, v52
	v_add_f32_e32 v45, 1.0, v45
	v_rcp_f32_e32 v45, v45
	v_add_f32_e32 v49, 1.0, v49
	v_rcp_f32_e32 v49, v49
	v_mul_f32_e32 v30, 0x3fb8aa3b, v30
	v_mul_f32_e32 v65, v45, v44
	v_and_b32_e32 v44, 0xffff0000, v50
	v_mul_f32_e32 v45, 0x3d372713, v44
	v_mul_f32_e32 v52, v49, v48
	v_and_b32_e32 v48, 0xffff0000, v53
	v_mul_f32_e32 v45, v45, v44
	v_mul_f32_e32 v49, 0x3d372713, v48
	v_fma_f32 v45, v45, v44, v44
	v_mul_f32_e32 v49, v49, v48
	v_mul_f32_e32 v45, 0x3fcc422a, v45
	v_fma_f32 v49, v49, v48, v48
	v_mul_f32_e32 v45, 0xbfb8aa3b, v45
	v_mul_f32_e32 v49, 0x3fcc422a, v49
	v_exp_f32_e32 v45, v45
	v_mul_f32_e32 v49, 0xbfb8aa3b, v49
	v_exp_f32_e32 v49, v49
	v_exp_f32_e32 v30, v30
	v_add_f32_e32 v45, 1.0, v45
	v_rcp_f32_e32 v45, v45
	v_add_f32_e32 v49, 1.0, v49
	v_rcp_f32_e32 v49, v49
	v_mul_f32_e32 v24, 0x3fb8aa3b, v24
	v_mul_f32_e32 v66, v45, v44
	v_lshlrev_b32_e32 v44, 16, v51
	v_exp_f32_e32 v24, v24
	v_mul_f32_e32 v28, 0x3fb8aa3b, v28
	v_mul_f32_e32 v44, 0x3fb8aa3b, v44
	v_mul_f32_e32 v53, v49, v48
	s_waitcnt vmcnt(2)
	v_lshlrev_b32_e32 v48, 16, v54
	v_exp_f32_e32 v28, v28
	v_mul_f32_e32 v40, 0x3fb8aa3b, v40
	v_exp_f32_e32 v45, v44
	v_and_b32_e32 v44, 0xffff0000, v51
	v_mul_f32_e32 v48, 0x3fb8aa3b, v48
	v_exp_f32_e32 v40, v40
	v_mul_f32_e32 v44, 0x3fb8aa3b, v44
	v_exp_f32_e32 v49, v48
	v_and_b32_e32 v48, 0xffff0000, v54
	v_exp_f32_e32 v44, v44
	v_mul_f32_e32 v48, 0x3fb8aa3b, v48
	v_pk_fma_f32 v[22:23], v[22:23], v[30:31], v[32:33]
	v_exp_f32_e32 v48, v48
	v_mul_f32_e32 v30, v23, v59
	v_mul_f32_e32 v31, v22, v60
	v_pk_fma_f32 v[22:23], v[22:23], v[24:25], v[26:27]
	v_cvt_pk_bf16_f32 v30, v30, v31
	s_waitcnt vmcnt(1)
	v_lshlrev_b32_e32 v51, 16, v55
	v_mul_f32_e32 v24, v23, v61
	v_mul_f32_e32 v25, v22, v62
	v_pk_fma_f32 v[22:23], v[22:23], v[28:29], v[38:39]
	v_cvt_pk_bf16_f32 v24, v24, v25
	v_and_b32_e32 v50, 0xffff0000, v55
	v_mul_f32_e32 v25, v23, v63
	v_mul_f32_e32 v26, v22, v64
	v_pk_fma_f32 v[22:23], v[22:23], v[40:41], v[42:43]
	v_cvt_pk_bf16_f32 v25, v25, v26
	s_nop 0
	v_mul_f32_e32 v26, v23, v65
	v_mul_f32_e32 v27, v22, v66
	v_pk_fma_f32 v[22:23], v[22:23], v[44:45], v[46:47]
	v_cvt_pk_bf16_f32 v26, v26, v27
	s_nop 0
	v_mul_f32_e32 v28, v22, v53
	v_pk_fma_f32 v[38:39], v[22:23], v[48:49], v[50:51]
	s_waitcnt vmcnt(0)
	v_lshlrev_b32_e32 v22, 16, v56
	v_mul_f32_e32 v27, v23, v52
	v_mul_f32_e32 v23, 0x3d372713, v22
	v_mul_f32_e32 v23, v23, v22
	v_fma_f32 v23, v23, v22, v22
	v_mul_f32_e32 v23, 0x3fcc422a, v23
	v_mul_f32_e32 v23, 0xbfb8aa3b, v23
	v_exp_f32_e32 v23, v23
	v_cvt_pk_bf16_f32 v27, v27, v28
	s_nop 0
	v_add_f32_e32 v23, 1.0, v23
	v_rcp_f32_e32 v23, v23
	s_nop 0
	v_mul_f32_e32 v22, v23, v22
	v_and_b32_e32 v23, 0xffff0000, v56
	v_mul_f32_e32 v28, 0x3d372713, v23
	v_mul_f32_e32 v28, v28, v23
	v_fma_f32 v28, v28, v23, v23
	v_mul_f32_e32 v28, 0x3fcc422a, v28
	v_mul_f32_e32 v28, 0xbfb8aa3b, v28
	v_exp_f32_e32 v28, v28
	v_mul_f32_e32 v22, v39, v22
	v_add_f32_e32 v28, 1.0, v28
	v_rcp_f32_e32 v28, v28
	s_nop 0
	v_mul_f32_e32 v23, v28, v23
	v_mul_f32_e32 v23, v38, v23
	v_cvt_pk_bf16_f32 v22, v22, v23
	global_store_dword v[6:7], v0, off
	global_store_dword v[8:9], v57, off offset:2048
	global_store_dword v[10:11], v30, off
	global_store_dword v[12:13], v24, off offset:2048
	global_store_dword v[14:15], v25, off
	global_store_dword v[16:17], v26, off offset:2048
	global_store_dword v[18:19], v27, off
	global_store_dword v[20:21], v22, off offset:2048
	s_cbranch_scc0 .LBB0_966
	v_add_u32_e32 v58, s101, v58
	v_readlane_b32 s16, v255, 50
	s_nop 0
	s_sub_u32 s16, s16, 1
	v_cmp_lt_i32_e32 vcc, s16, v58
	s_or_b64 s[14:15], vcc, s[14:15]
	s_andn2_b64 exec, exec, s[14:15]
	s_cbranch_execnz .LBB0_947
.Lscan2_done:
	s_or_b64 exec, exec, s[4:5]
	s_cmp_eq_u32 s101, 0xfc00
	s_cbranch_scc1 .Lscan2_ret
	s_branch .Lscan2_skip
.LBB0_968:
	s_or_b64 exec, exec, s[4:5]
.Lscan2_skip:
	s_waitcnt vmcnt(0)
	s_barrier
	s_mov_b64 s[0:1], exec
	v_readlane_b32 s4, v252, 2
	v_readlane_b32 s5, v252, 3
	s_and_b64 s[4:5], s[0:1], s[4:5]
	s_mov_b64 exec, s[4:5]
	s_cbranch_execz .LBB0_1020
	v_readlane_b32 s4, v254, 18
	s_waitcnt vmcnt(0) expcnt(0) lgkmcnt(0)
	s_nop 0
	v_mov_b32_e32 v0, s4
	ds_read_b32 v3, v0
	v_readlane_b32 s4, v254, 19
	s_waitcnt lgkmcnt(0)
	v_cmp_ne_u32_e32 vcc, 0, v3
	v_mov_b32_e32 v0, s4
	ds_read_b32 v2, v0
	s_cbranch_vccnz .LBB0_984
	s_mov_b32 s18, 1
	s_branch .LBB0_972

; #define PG8_STAGE(bufoff, gbase, voff) do { _Pragma("unroll") for (int _i = 0; _i < 2; ++_i) \
;         __builtin_amdgcn_global_load_lds((const unsigned*)((const char*)(gbase) + (voff)[_i]), (LAS unsigned*)(lds + (bufoff) + ldsw + _i * 8192), 16, 0, 0); } while (0)
; #define PG8_WAIT_V(n) asm volatile("s_waitcnt vmcnt(" #n ")" ::: "memory")
; template <class Epi, class Sched>
; __device__ __forceinline__ void gemm_phase(LAS unsigned char* lds, const int lda, const int ldb, const Sched& S, const Epi& E) {
;     ...
;     const int tid = tid_, wid = __builtin_amdgcn_readfirstlane(tid >> 6), lane = tid & 63, wr = wid >> 2, wc = wid & 3, fr = lane & 15, fq = lane >> 4;
;     unsigned voffA[2], voffB[2];
; #pragma unroll
;     for (int i = 0; i < 2; ++i) { int R, C; stage_rc(tid * 16 + i * 8192, R, C); const int Rb = Epi::PERM ? ((R & ~31) + perm32(R & 31)) : R;
;         voffA[i] = (unsigned)(R * lda + C) * 2u; voffB[i] = (unsigned)(Rb * ldb + C) * 2u; }
;     const size_t kstep = (size_t)(BK * 2);
;     const size_t hstepA = (size_t)HALF * lda * 2, hstepB = (size_t)HALF * ldb * 2;
;     const unsigned ldsw = (unsigned)wid * 1024u;
;     const int aoff = lds_byte(wr * 64 + fr, fq * 8), boff = lds_byte(wc * 32 + fr, fq * 8);
;     ...
;     Unit cur, nxt; int ui = 0;
;     if (!S.next(0, cur)) return;
;     f32x4 acc[2][2][4][2];
; #pragma unroll
;     for (int a = 0; a < 2; ++a)
; #pragma unroll
;         for (int b = 0; b < 2; ++b)
; #pragma unroll
;             for (int m = 0; m < 4; ++m)
; #pragma unroll
;                 for (int n = 0; n < 2; ++n) acc[a][b][m][n] = (f32x4){0.f, 0.f, 0.f, 0.f};
;     bf16x8 At[4][2], B0[2][2], B1[2][2];
;     const char* cA = cur.A; const char* cB = cur.B; asm volatile("" : "+s"(cA), "+s"(cB));
;     PG8_STAGE(PG8_SB(0, 0), cB, voffB); PG8_STAGE(PG8_SB(0, 1), cB + hstepB, voffB); PG8_STAGE(PG8_SA(0, 0), cA, voffA); PG8_STAGE(PG8_SA(0, 1), cA + hstepA, voffA);
;     if (wr == 1) PG8_BAR;
;     PG8_WAIT_V(2); PG8_BAR;
;     PG8_STAGE(PG8_SB(1, 0), cB + kstep, voffB); PG8_STAGE(PG8_SA(1, 0), cA + kstep, voffA); PG8_STAGE(PG8_SB(1, 1), cB + hstepB + kstep, voffB);
; __global__ void __launch_bounds__(512, 2) mega_fwd(Params P) {
;     ...
;         PH(9) { PHASE_BEGIN
;           pg8::DenseOrder S{P5 + C_V, WGLU, LDP, 1024, MP / 256, 4, G, c, 16}; pg8::EpiGlu E{P5, PIN(I_S5BG) + (size_t)l * 1024};
;           pg8::gemm_phase(lds, LDP, 1024, S, E); }
.LBB0_1020:
	s_or_b64 exec, exec, s[0:1]
	v_mov_b32_e32 v0, v163
	s_waitcnt lgkmcnt(0)
	v_mov_b32_e32 v2, v162
	s_barrier
	v_readlane_b32 s14, v253, 28
	v_readfirstlane_b32 s5, v0
	v_mov_b32_e32 v0, v1
	v_mov_b32_e32 v18, v208
	v_readlane_b32 s15, v253, 29
	v_readfirstlane_b32 s4, v2
	s_andn2_b64 vcc, exec, s[14:15]
	v_readfirstlane_b32 s0, v0
	v_readfirstlane_b32 s16, v18
	s_cbranch_vccnz .LBB0_1040
	s_cmpk_lt_u32 s2, 0x82
	s_cbranch_scc1 .Lglu_go
	v_writelane_b32 v255, s0, 8
	s_nop 1
	v_writelane_b32 v255, s1, 9
	s_nop 1
	v_writelane_b32 v255, s4, 10
	s_nop 1
	v_writelane_b32 v255, s5, 11
	s_nop 1
	v_writelane_b32 v255, s14, 12
	s_nop 1
	v_writelane_b32 v255, s15, 13
	s_nop 1
	v_writelane_b32 v255, s16, 14
	s_nop 1
	v_writelane_b32 v255, s17, 15
	s_nop 1
	v_writelane_b32 v255, s18, 16
	s_nop 1
	v_writelane_b32 v255, s19, 17
	s_nop 1
	v_writelane_b32 v255, s24, 18
	s_nop 1
	v_writelane_b32 v255, s25, 19
	s_nop 1
	v_writelane_b32 v255, s28, 20
	s_nop 1
	v_writelane_b32 v255, s32, 21
	s_nop 1
	v_writelane_b32 v255, s42, 22
	s_nop 1
	v_writelane_b32 v255, s50, 23
	s_nop 1
	v_writelane_b32 v255, s51, 24
	s_nop 1
	s_sub_u32 s100, s2, 0x82
	s_lshl_b32 s100, s100, 9
	s_add_u32 s100, s100, 0x10000
	s_mov_b32 s101, 0xfc00
	s_mov_b32 s4, 0x20800
	v_writelane_b32 v255, s4, 50
	s_nop 1
	s_branch .Lscan2_entry
.Lscan2_ret:
	s_mov_b64 exec, -1
	s_waitcnt vmcnt(0) lgkmcnt(0)
	v_readlane_b32 s0, v255, 8
	v_readlane_b32 s1, v255, 9
	v_readlane_b32 s4, v255, 10
	v_readlane_b32 s5, v255, 11
	v_readlane_b32 s14, v255, 12
	v_readlane_b32 s15, v255, 13
	v_readlane_b32 s16, v255, 14
	v_readlane_b32 s17, v255, 15
	v_readlane_b32 s18, v255, 16
	v_readlane_b32 s19, v255, 17
	v_readlane_b32 s24, v255, 18
	v_readlane_b32 s25, v255, 19
	v_readlane_b32 s28, v255, 20
	v_readlane_b32 s32, v255, 21
	v_readlane_b32 s42, v255, 22
	v_readlane_b32 s50, v255, 23
	v_readlane_b32 s51, v255, 24
	s_nop 4
	s_branch .LBB0_1040
.Lglu_go:
	v_lshlrev_b32_e32 v0, 4, v18
	v_add_u32_e32 v2, 0x2000, v0
	v_ashrrev_i32_e32 v3, 31, v2
	v_lshrrev_b32_e32 v3, 22, v3
	v_add_u32_e32 v3, v2, v3
	v_ashrrev_i32_e32 v10, 10, v3
	v_mul_i32_i24_e32 v3, 0x400, v10
	v_sub_u32_e32 v2, v2, v3
	s_add_u32 s30, s4, 0x8902000
	v_lshrrev_b32_e32 v3, 4, v2
	s_addc_u32 s31, s5, 0
	v_bitop3_b32 v2, v3, v2, 32 bitop3:0x6c
	s_add_u32 s46, s4, 0x4400000
	v_ashrrev_i32_e32 v3, 31, v2
	s_addc_u32 s47, s5, 0
	s_ashr_i32 s1, s0, 31
	v_lshrrev_b32_e32 v3, 26, v3
	s_lshl_b64 s[0:1], s[0:1], 3
	v_readlane_b32 s14, v254, 30
	v_add_u32_e32 v3, v2, v3
	v_lshlrev_b32_e32 v4, 3, v10
	v_readlane_b32 s15, v254, 31
	s_add_u32 s0, s14, s0
	v_ashrrev_i32_e32 v11, 6, v3
	v_and_b32_e32 v4, -16, v4
	s_addc_u32 s1, s15, s1
	v_add_u32_e32 v4, v11, v4
	s_load_dwordx2 s[14:15], s[0:1], 0xb8
	v_and_b32_e32 v5, 3, v11
	s_mov_b32 s1, 0x1fffe0
	v_lshrrev_b32_e32 v6, 2, v4
	v_lshlrev_b32_e32 v7, 1, v4
	v_and_or_b32 v5, v4, s1, v5
	v_and_b32_e32 v6, 4, v6
	v_and_b32_e32 v7, 24, v7
	v_and_b32_e32 v3, 0xc0, v3
	v_or3_b32 v5, v5, v6, v7
	v_sub_u32_e32 v2, v2, v3
	v_mov_b32_e32 v7, 1
	v_lshlrev_b32_e32 v6, 5, v10
	v_ashrrev_i16_sdwa v2, v7, sext(v2) dst_sel:DWORD dst_unused:UNUSED_PAD src0_sel:DWORD src1_sel:BYTE_0
	v_and_b32_e32 v12, 32, v6
	v_bfe_i32 v13, v2, 0, 16
	v_add_u32_e32 v2, v12, v13
	v_lshlrev_b32_e32 v3, 1, v2
	s_movk_i32 s0, 0x1400
	v_lshl_add_u32 v158, v5, 11, v3
	v_mul_lo_u32 v3, v4, s0
	v_add_lshl_u32 v160, v2, v3, 1
	v_bfe_i32 v2, v18, 27, 1
	v_lshrrev_b32_e32 v2, 22, v2
	v_add_u32_e32 v2, v0, v2
	v_and_b32_e32 v2, 0xfffffc00, v2
	v_sub_u32_e32 v0, v0, v2
	v_lshrrev_b32_e32 v2, 4, v0
	v_ashrrev_i32_e32 v3, 31, v18
	v_bitop3_b32 v0, v2, v0, 32 bitop3:0x6c
	v_lshrrev_b32_e32 v3, 26, v3
	v_ashrrev_i32_e32 v2, 31, v0
	v_add_u32_e32 v3, v18, v3
	v_lshrrev_b32_e32 v2, 26, v2
	v_ashrrev_i32_e32 v15, 6, v3
	v_add_u32_e32 v2, v0, v2
	v_lshlrev_b32_e32 v3, 3, v15
	v_ashrrev_i32_e32 v14, 6, v2
	v_and_b32_e32 v3, -16, v3
	s_ashr_i32 s17, s16, 6
	v_add_u32_e32 v3, v14, v3
	v_and_b32_e32 v4, 3, v14
	s_ashr_i32 s18, s16, 8
	s_lshl_b32 s48, s17, 10
	v_and_or_b32 v4, v3, s1, v4
	v_lshrrev_b32_e32 v5, 2, v3
	v_lshlrev_b32_e32 v6, 1, v3
	v_and_b32_e32 v2, 0xc0, v2
	v_mul_lo_u32 v3, v3, s0
	v_readlane_b32 s0, v253, 55
	v_and_b32_e32 v5, 4, v5
	v_and_b32_e32 v6, 24, v6
	v_sub_u32_e32 v0, v0, v2
	v_readlane_b32 s1, v253, 56
	s_add_u32 s40, s46, s0
	v_or3_b32 v4, v4, v5, v6
	v_lshlrev_b32_e32 v5, 5, v15
	v_ashrrev_i16_sdwa v0, v7, sext(v0) dst_sel:DWORD dst_unused:UNUSED_PAD src0_sel:DWORD src1_sel:BYTE_0
	s_addc_u32 s41, s47, s1
	v_readlane_b32 s1, v253, 54
	v_and_b32_e32 v16, 32, v5
	v_bfe_i32 v17, v0, 0, 16
	s_mul_i32 s0, s1, 0x280000
	v_add_u32_e32 v2, v16, v17
	s_add_u32 s34, s30, s0
	s_mul_hi_i32 s0, s1, 0x280000
	v_lshlrev_b32_e32 v0, 1, v2
	s_addc_u32 s35, s31, s0
	s_add_i32 s49, s48, 0
	v_lshl_add_u32 v0, v4, 11, v0
	s_add_i32 m0, s49, 0x10000
	v_add_lshl_u32 v166, v2, v3, 1
	global_load_lds_dwordx4 v0, s[40:41]
	s_add_i32 m0, s49, 0x12000
	s_add_u32 s0, s40, 0x40000
	global_load_lds_dwordx4 v158, s[40:41]
	s_addc_u32 s1, s41, 0
	s_add_i32 m0, s49, 0x14000
	s_add_i32 s50, s49, 0x2000
	global_load_lds_dwordx4 v0, s[0:1]
	s_add_i32 m0, s49, 0x16000
	v_mov_b32_e32 v159, v1
	global_load_lds_dwordx4 v158, s[0:1]
	s_mov_b32 m0, s49
	s_add_u32 s0, s34, 0x140000
	global_load_lds_dwordx4 v166, s[34:35]
	s_mov_b32 m0, s50
	s_addc_u32 s1, s35, 0
	s_add_i32 s51, s49, 0x4000
	global_load_lds_dwordx4 v160, s[34:35]
	s_mov_b32 m0, s51
	s_add_i32 s52, s49, 0x6000
	global_load_lds_dwordx4 v166, s[0:1]
	s_mov_b32 m0, s52
	v_mov_b32_e32 v167, v1
	global_load_lds_dwordx4 v160, s[0:1]
	v_mov_b32_e32 v161, v1
	s_cmp_eq_u32 s18, 1
	v_lshl_add_u64 v[8:9], s[40:41], 0, v[0:1]
	v_lshl_add_u64 v[6:7], s[40:41], 0, v[158:159]
	v_lshl_add_u64 v[2:3], s[34:35], 0, v[166:167]
	s_cselect_b64 s[0:1], -1, 0
	s_cmp_lg_u32 s18, 1
	v_lshl_add_u64 v[4:5], s[34:35], 0, v[160:161]
	s_cbranch_scc1 .LBB0_1023
	s_barrier

;     __device__ __forceinline__ bool next(int i, Unit& u) const {
;         const int L = i * G + c; if (L >= nM * nN) return false;
;         int pm, pn; dense_tile(L, nM, nN, pm, pn);
;         u.pm = pm; u.pn = pn; u.aux = 0; u.nt = ntk;
;         u.A = (const char*)(A + (size_t)pm * 256 * lda); u.B = (const char*)(Bt + (size_t)pn * 256 * ldb); return true;
.LBB0_1026:
	s_add_i32 s55, s55, 1
	s_mul_i32 s42, s55, 0x82
	s_add_i32 s42, s42, s2
	s_cmpk_lt_i32 s42, 0x104
	s_cselect_b64 s[18:19], -1, 0
	s_cmpk_gt_i32 s42, 0x103
	s_cbranch_scc1 .LBB0_1032
	s_ashr_i32 s24, s42, 31
	s_lshr_b32 s24, s24, 29
	s_add_i32 s28, s42, s24
	s_and_b32 s24, s28, -8
	s_sub_i32 s29, s42, s24
	s_cmp_gt_i32 s29, 3
	s_mov_b64 s[24:25], -1
	s_cbranch_scc0 .LBB0_1029
	s_lshl_b32 s24, s29, 5
	s_or_b32 s42, s24, 4
	s_mov_b64 s[24:25], 0

; __global__ void __launch_bounds__(512, 2) mega_fwd(Params P) {
	.amdhsa_kernel _Z8mega_fwd6Params
		.amdhsa_group_segment_fixed_size 0
		.amdhsa_private_segment_fixed_size 0
		.amdhsa_kernarg_size 504
		.amdhsa_user_sgpr_count 2
		.amdhsa_user_sgpr_dispatch_ptr 0
		.amdhsa_user_sgpr_queue_ptr 0
		.amdhsa_user_sgpr_kernarg_segment_ptr 1
		.amdhsa_user_sgpr_dispatch_id 0
		.amdhsa_user_sgpr_kernarg_preload_length 0
		.amdhsa_user_sgpr_kernarg_preload_offset 0
		.amdhsa_user_sgpr_private_segment_size 0
		.amdhsa_uses_dynamic_stack 0
		.amdhsa_enable_private_segment 0
		.amdhsa_system_sgpr_workgroup_id_x 1
		.amdhsa_system_sgpr_workgroup_id_y 0
		.amdhsa_system_sgpr_workgroup_id_z 0
		.amdhsa_system_sgpr_workgroup_info 0
		.amdhsa_system_vgpr_workitem_id 2
		.amdhsa_next_free_vgpr 256
		.amdhsa_next_free_sgpr 102
		.amdhsa_accum_offset 256
		.amdhsa_reserve_vcc 1
		.amdhsa_float_round_mode_32 0
		.amdhsa_float_round_mode_16_64 0
		.amdhsa_float_denorm_mode_32 3
		.amdhsa_float_denorm_mode_16_64 3
		.amdhsa_dx10_clamp 1
		.amdhsa_ieee_mode 1
		.amdhsa_fp16_overflow 0
		.amdhsa_tg_split 0
		.amdhsa_exception_fp_ieee_invalid_op 0
		.amdhsa_exception_fp_denorm_src 0
		.amdhsa_exception_fp_ieee_div_zero 0
		.amdhsa_exception_fp_ieee_overflow 0
		.amdhsa_exception_fp_ieee_underflow 0
		.amdhsa_exception_fp_ieee_inexact 0
		.amdhsa_exception_int_div_zero 0
	.end_amdhsa_kernel

; __global__ void __launch_bounds__(512, 2) mega_fwd(Params P) {
amdhsa.kernels:
  - .agpr_count:     0
    .args:
      - .offset:         0
        .size:           248
        .value_kind:     by_value
      - .offset:         248
        .size:           4
        .value_kind:     hidden_block_count_x
      - .offset:         252
        .size:           4
        .value_kind:     hidden_block_count_y
      - .offset:         256
        .size:           4
        .value_kind:     hidden_block_count_z
      - .offset:         260
        .size:           2
        .value_kind:     hidden_group_size_x
      - .offset:         262
        .size:           2
        .value_kind:     hidden_group_size_y
      - .offset:         264
        .size:           2
        .value_kind:     hidden_group_size_z
      - .offset:         266
        .size:           2
        .value_kind:     hidden_remainder_x
      - .offset:         268
        .size:           2
        .value_kind:     hidden_remainder_y
      - .offset:         270
        .size:           2
        .value_kind:     hidden_remainder_z
      - .offset:         288
        .size:           8
        .value_kind:     hidden_global_offset_x
      - .offset:         296
        .size:           8
        .value_kind:     hidden_global_offset_y
      - .offset:         304
        .size:           8
        .value_kind:     hidden_global_offset_z
      - .offset:         312
        .size:           2
        .value_kind:     hidden_grid_dims
      - .offset:         336
        .size:           8
        .value_kind:     hidden_multigrid_sync_arg
      - .offset:         368
        .size:           4
        .value_kind:     hidden_dynamic_lds_size
    .group_segment_fixed_size: 0
    .kernarg_segment_align: 8
    .kernarg_segment_size: 504
    .language:       OpenCL C
    .language_version:
      - 2
      - 0
    .max_flat_workgroup_size: 512
    .name:           _Z8mega_fwd6Params
    .private_segment_fixed_size: 0
    .sgpr_count:     108
    .sgpr_spill_count: 200
    .symbol:         _Z8mega_fwd6Params.kd
    .uniform_work_group_size: 1
    .uses_dynamic_stack: false
    .vgpr_count:     256
    .vgpr_spill_count: 0
    .wavefront_size: 64
